# HGRN gate prologue: max(-x,-x)+min(60) pair folded into one v_min with an SGPR constant (16 VALU fewer per wave-item)
# speedup vs baseline: 1.0010x; 1.0010x over previous
.LBB0_234:
	s_mov_b32 s100, 0x42700000
	v_sub_f32_e32 v204, 1.0, v36
	v_lshlrev_b32_e32 v40, 16, v40
	v_lshlrev_b32_e32 v51, 16, v51
	v_lshlrev_b32_e32 v50, 16, v50
	v_lshlrev_b32_e32 v49, 16, v49
	v_min_f32_e64 v186, -v40, s100
	v_min_f32_e64 v190, -v51, s100
	v_min_f32_e64 v194, -v50, s100
	v_min_f32_e64 v198, -v49, s100
	v_mul_f32_e32 v186, 0x3fb8aa3b, v186
	v_mul_f32_e32 v190, 0x3fb8aa3b, v190
	v_mul_f32_e32 v194, 0x3fb8aa3b, v194
	v_mul_f32_e32 v198, 0x3fb8aa3b, v198
	v_exp_f32_e32 v186, v186
	v_exp_f32_e32 v190, v190
	v_exp_f32_e32 v194, v194
	v_exp_f32_e32 v198, v198
	v_add_f32_e32 v187, 1.0, v186
	v_add_f32_e32 v191, 1.0, v190
	v_add_f32_e32 v195, 1.0, v194
	v_add_f32_e32 v199, 1.0, v198
	v_fma_f32 v189, v186, v36, 1.0
	v_fma_f32 v193, v190, v36, 1.0
	v_fma_f32 v197, v194, v36, 1.0
	v_fma_f32 v201, v198, v36, 1.0
	v_rcp_f32_e32 v188, v187
	v_rcp_f32_e32 v192, v191
	v_rcp_f32_e32 v196, v195
	v_rcp_f32_e32 v200, v199
	v_log_f32_e32 v187, v187
	v_log_f32_e32 v191, v191
	v_log_f32_e32 v195, v195
	v_log_f32_e32 v199, v199
	v_log_f32_e32 v189, v189
	v_log_f32_e32 v193, v193
	v_log_f32_e32 v197, v197
	v_log_f32_e32 v201, v201
	v_mul_f32_e32 v188, v186, v188
	v_mul_f32_e32 v192, v190, v192
	v_mul_f32_e32 v196, v194, v196
	v_mul_f32_e32 v200, v198, v200
	v_mul_f32_e32 v187, 0xbf317218, v187
	v_mul_f32_e32 v191, 0xbf317218, v191
	v_mul_f32_e32 v195, 0xbf317218, v195
	v_mul_f32_e32 v199, 0xbf317218, v199
	v_mul_f32_e32 v144, v188, v204
	v_mul_f32_e32 v145, v192, v204
	v_mul_f32_e32 v146, v196, v204
	v_mul_f32_e32 v147, v200, v204
	v_min_f32_e32 v187, v40, v187
	v_min_f32_e32 v191, v51, v191
	v_min_f32_e32 v195, v50, v195
	v_min_f32_e32 v199, v49, v199
	v_fmac_f32_e32 v187, 0x3f317218, v189
	v_fmac_f32_e32 v191, 0x3f317218, v193
	v_fmac_f32_e32 v195, 0x3f317218, v197
	v_fmac_f32_e32 v199, 0x3f317218, v201
	v_add_f32_e32 v128, 0, v187
	v_add_f32_e32 v129, v191, v128
	v_add_f32_e32 v130, v195, v129
	v_add_f32_e32 v131, v199, v130
	v_lshlrev_b32_e32 v48, 16, v48
	v_lshlrev_b32_e32 v47, 16, v47
	v_lshlrev_b32_e32 v46, 16, v46
	v_lshlrev_b32_e32 v45, 16, v45
	v_min_f32_e64 v186, -v48, s100
	v_min_f32_e64 v190, -v47, s100
	v_min_f32_e64 v194, -v46, s100
	v_min_f32_e64 v198, -v45, s100
	v_mul_f32_e32 v186, 0x3fb8aa3b, v186
	v_mul_f32_e32 v190, 0x3fb8aa3b, v190
	v_mul_f32_e32 v194, 0x3fb8aa3b, v194
	v_mul_f32_e32 v198, 0x3fb8aa3b, v198
	v_exp_f32_e32 v186, v186
	v_exp_f32_e32 v190, v190
	v_exp_f32_e32 v194, v194
	v_exp_f32_e32 v198, v198
	v_add_f32_e32 v187, 1.0, v186
	v_add_f32_e32 v191, 1.0, v190
	v_add_f32_e32 v195, 1.0, v194
	v_add_f32_e32 v199, 1.0, v198
	v_fma_f32 v189, v186, v36, 1.0
	v_fma_f32 v193, v190, v36, 1.0
	v_fma_f32 v197, v194, v36, 1.0
	v_fma_f32 v201, v198, v36, 1.0
	v_rcp_f32_e32 v188, v187
	v_rcp_f32_e32 v192, v191
	v_rcp_f32_e32 v196, v195
	v_rcp_f32_e32 v200, v199
	v_log_f32_e32 v187, v187
	v_log_f32_e32 v191, v191
	v_log_f32_e32 v195, v195
	v_log_f32_e32 v199, v199
	v_log_f32_e32 v189, v189
	v_log_f32_e32 v193, v193
	v_log_f32_e32 v197, v197
	v_log_f32_e32 v201, v201
	v_mul_f32_e32 v188, v186, v188
	v_mul_f32_e32 v192, v190, v192
	v_mul_f32_e32 v196, v194, v196
	v_mul_f32_e32 v200, v198, v200
	v_mul_f32_e32 v187, 0xbf317218, v187
	v_mul_f32_e32 v191, 0xbf317218, v191
	v_mul_f32_e32 v195, 0xbf317218, v195
	v_mul_f32_e32 v199, 0xbf317218, v199
	v_mul_f32_e32 v148, v188, v204
	v_mul_f32_e32 v149, v192, v204
	v_mul_f32_e32 v150, v196, v204
	v_mul_f32_e32 v151, v200, v204
	v_min_f32_e32 v187, v48, v187
	v_min_f32_e32 v191, v47, v191
	v_min_f32_e32 v195, v46, v195
	v_min_f32_e32 v199, v45, v199
	v_fmac_f32_e32 v187, 0x3f317218, v189
	v_fmac_f32_e32 v191, 0x3f317218, v193
	v_fmac_f32_e32 v195, 0x3f317218, v197
	v_fmac_f32_e32 v199, 0x3f317218, v201
	v_add_f32_e32 v132, v187, v131
	v_add_f32_e32 v133, v191, v132
	v_add_f32_e32 v134, v195, v133
	v_add_f32_e32 v135, v199, v134
	v_lshlrev_b32_e32 v44, 16, v44
	v_lshlrev_b32_e32 v43, 16, v43
	v_lshlrev_b32_e32 v42, 16, v42
	v_lshlrev_b32_e32 v41, 16, v41
	v_min_f32_e64 v186, -v44, s100
	v_min_f32_e64 v190, -v43, s100
	v_min_f32_e64 v194, -v42, s100
	v_min_f32_e64 v198, -v41, s100
	v_mul_f32_e32 v186, 0x3fb8aa3b, v186
	v_mul_f32_e32 v190, 0x3fb8aa3b, v190
	v_mul_f32_e32 v194, 0x3fb8aa3b, v194
	v_mul_f32_e32 v198, 0x3fb8aa3b, v198
	v_exp_f32_e32 v186, v186
	v_exp_f32_e32 v190, v190
	v_exp_f32_e32 v194, v194
	v_exp_f32_e32 v198, v198
	v_add_f32_e32 v187, 1.0, v186
	v_add_f32_e32 v191, 1.0, v190
	v_add_f32_e32 v195, 1.0, v194
	v_add_f32_e32 v199, 1.0, v198
	v_fma_f32 v189, v186, v36, 1.0
	v_fma_f32 v193, v190, v36, 1.0
	v_fma_f32 v197, v194, v36, 1.0
	v_fma_f32 v201, v198, v36, 1.0
	v_rcp_f32_e32 v188, v187
	v_rcp_f32_e32 v192, v191
	v_rcp_f32_e32 v196, v195
	v_rcp_f32_e32 v200, v199
	v_log_f32_e32 v187, v187
	v_log_f32_e32 v191, v191
	v_log_f32_e32 v195, v195
	v_log_f32_e32 v199, v199
	v_log_f32_e32 v189, v189
	v_log_f32_e32 v193, v193
	v_log_f32_e32 v197, v197
	v_log_f32_e32 v201, v201
	v_mul_f32_e32 v188, v186, v188
	v_mul_f32_e32 v192, v190, v192
	v_mul_f32_e32 v196, v194, v196
	v_mul_f32_e32 v200, v198, v200
	v_mul_f32_e32 v187, 0xbf317218, v187
	v_mul_f32_e32 v191, 0xbf317218, v191
	v_mul_f32_e32 v195, 0xbf317218, v195
	v_mul_f32_e32 v199, 0xbf317218, v199
	v_mul_f32_e32 v152, v188, v204
	v_mul_f32_e32 v153, v192, v204
	v_mul_f32_e32 v154, v196, v204
	v_mul_f32_e32 v155, v200, v204
	v_min_f32_e32 v187, v44, v187
	v_min_f32_e32 v191, v43, v191
	v_min_f32_e32 v195, v42, v195
	v_min_f32_e32 v199, v41, v199
	v_fmac_f32_e32 v187, 0x3f317218, v189
	v_fmac_f32_e32 v191, 0x3f317218, v193
	v_fmac_f32_e32 v195, 0x3f317218, v197
	v_fmac_f32_e32 v199, 0x3f317218, v201
	v_add_f32_e32 v136, v187, v135
	v_add_f32_e32 v137, v191, v136
	v_add_f32_e32 v138, v195, v137
	v_add_f32_e32 v139, v199, v138
	v_lshlrev_b32_e32 v39, 16, v39
	v_lshlrev_b32_e32 v38, 16, v38
	v_lshlrev_b32_e32 v37, 16, v37
	v_lshlrev_b32_e32 v35, 16, v35
	v_min_f32_e64 v186, -v39, s100
	v_min_f32_e64 v190, -v38, s100
	v_min_f32_e64 v194, -v37, s100
	v_min_f32_e64 v198, -v35, s100
	v_mul_f32_e32 v186, 0x3fb8aa3b, v186
	v_mul_f32_e32 v190, 0x3fb8aa3b, v190
	v_mul_f32_e32 v194, 0x3fb8aa3b, v194
	v_mul_f32_e32 v198, 0x3fb8aa3b, v198
	v_exp_f32_e32 v186, v186
	v_exp_f32_e32 v190, v190
	v_exp_f32_e32 v194, v194
	v_exp_f32_e32 v198, v198
	v_add_f32_e32 v187, 1.0, v186
	v_add_f32_e32 v191, 1.0, v190
	v_add_f32_e32 v195, 1.0, v194
	v_add_f32_e32 v199, 1.0, v198
	v_fma_f32 v189, v186, v36, 1.0
	v_fma_f32 v193, v190, v36, 1.0
	v_fma_f32 v197, v194, v36, 1.0
	v_fma_f32 v201, v198, v36, 1.0
	v_rcp_f32_e32 v188, v187
	v_rcp_f32_e32 v192, v191
	v_rcp_f32_e32 v196, v195
	v_rcp_f32_e32 v200, v199
	v_log_f32_e32 v187, v187
	v_log_f32_e32 v191, v191
	v_log_f32_e32 v195, v195
	v_log_f32_e32 v199, v199
	v_log_f32_e32 v189, v189
	v_log_f32_e32 v193, v193
	v_log_f32_e32 v197, v197
	v_log_f32_e32 v201, v201
	v_mul_f32_e32 v188, v186, v188
	v_mul_f32_e32 v192, v190, v192
	v_mul_f32_e32 v196, v194, v196
	v_mul_f32_e32 v200, v198, v200
	v_mul_f32_e32 v187, 0xbf317218, v187
	v_mul_f32_e32 v191, 0xbf317218, v191
	v_mul_f32_e32 v195, 0xbf317218, v195
	v_mul_f32_e32 v199, 0xbf317218, v199
	v_mul_f32_e32 v156, v188, v204
	v_mul_f32_e32 v157, v192, v204
	v_mul_f32_e32 v158, v196, v204
	v_mul_f32_e32 v159, v200, v204
	v_min_f32_e32 v187, v39, v187
	v_min_f32_e32 v191, v38, v191
	v_min_f32_e32 v195, v37, v195
	v_min_f32_e32 v199, v35, v199
	v_fmac_f32_e32 v187, 0x3f317218, v189
	v_fmac_f32_e32 v191, 0x3f317218, v193
	v_fmac_f32_e32 v195, 0x3f317218, v197
	v_fmac_f32_e32 v199, 0x3f317218, v201
	v_add_f32_e32 v140, v187, v139
	v_add_f32_e32 v141, v191, v140
	v_add_f32_e32 v142, v195, v141
	v_add_f32_e32 v143, v199, v142
	s_mov_b32 s3, 0xbfb8aa3b
	v_lshrrev_b32_e32 v28, 8, v28
	s_movk_i32 s2, 0x410
	v_mul_i32_i24_e32 v28, 0xd800, v28
	v_mad_u32_u24 v40, v29, s2, v21
	v_lshl_add_u32 v40, v40, 2, v28
	v_mov_b32_e32 v160, v40
	v_add_u32_e32 v52, 0x4400, v40
	v_and_b32_e32 v33, 0xff, v33
	v_mul_u32_u24_e32 v31, 0x48, v31
	v_add_u32_e32 v51, 0x400, v40
	v_add_u32_e32 v49, 0x4800, v40
	v_lshlrev_b32_e32 v31, 1, v31
	v_lshlrev_b32_e32 v30, 1, v30
	v_cmp_lt_u32_e32 vcc, 63, v33
	s_nop 0
	v_add_u32_e32 v47, 0x800, v40
	v_add_u32_e32 v45, 0x4c00, v40
	s_nop 0
	s_nop 0
	v_add_u32_e32 v43, 0xc00, v40
	v_add_u32_e32 v40, 0x5000, v40
	v_lshl_add_u32 v34, v33, 2, v28
	v_add_u32_e32 v161, 0x400, v160
	v_add_u32_e32 v162, 0x800, v160
	v_add_u32_e32 v163, 0xc00, v160
	v_add_u32_e32 v164, 0x4400, v160
	v_add_u32_e32 v165, 0x4800, v160
	v_add_u32_e32 v166, 0x4c00, v160
	v_add_u32_e32 v167, 0x5000, v160
	ds_write2_b32 v160, v128, v129 offset1:65
	ds_write2_b32 v164, v144, v145 offset1:65
	ds_write2_b32 v160, v130, v131 offset0:130 offset1:195
	ds_write2_b32 v164, v146, v147 offset0:130 offset1:195
	ds_write2_b32 v161, v132, v133 offset0:4 offset1:69
	ds_write2_b32 v165, v148, v149 offset0:4 offset1:69
	ds_write2_b32 v161, v134, v135 offset0:134 offset1:199
	ds_write2_b32 v165, v150, v151 offset0:134 offset1:199
	ds_write2_b32 v162, v136, v137 offset0:8 offset1:73
	ds_write2_b32 v166, v152, v153 offset0:8 offset1:73
	ds_write2_b32 v162, v138, v139 offset0:138 offset1:203
	ds_write2_b32 v166, v154, v155 offset0:138 offset1:203
	ds_write2_b32 v167, v156, v157 offset0:12 offset1:77
	ds_write2_b32 v163, v140, v141 offset0:12 offset1:77
	ds_write2_b32 v163, v142, v143 offset0:142 offset1:207
	ds_write2_b32 v167, v158, v159 offset0:142 offset1:207
	ds_write_b32 v34, v143 offset:53248
	v_add3_u32 v34, v28, v31, v30
	v_add3_u32 v30, v28, v30, v31
	ds_write_b16 v34, v12 offset:34816
	ds_write_b16_d16_hi v30, v12 offset:34960
	ds_write_b16 v34, v13 offset:35104
	ds_write_b16_d16_hi v30, v13 offset:35248
	ds_write_b16 v34, v14 offset:35392
	ds_write_b16_d16_hi v30, v14 offset:35536
	ds_write_b16 v34, v15 offset:35680
	ds_write_b16_d16_hi v30, v15 offset:35824
	ds_write_b16 v34, v8 offset:35968
	ds_write_b16_d16_hi v30, v8 offset:36112
	ds_write_b16 v34, v9 offset:36256
	ds_write_b16_d16_hi v30, v9 offset:36400
	ds_write_b16 v34, v10 offset:36544
	ds_write_b16_d16_hi v30, v10 offset:36688
	ds_write_b16 v34, v11 offset:36832
	ds_write_b16_d16_hi v30, v11 offset:36976
	s_waitcnt lgkmcnt(0)
	s_barrier
	s_and_saveexec_b64 s[2:3], vcc
	s_cbranch_execz .LBB0_238
	v_lshlrev_b32_e32 v8, 2, v21
	s_mov_b32 s4, 0xd000
	v_add3_u32 v8, v28, v8, s4
	v_mov_b32_e32 v20, 0
	s_mov_b64 s[4:5], 0
